# ssm pass-3: hoisted the 8 serialized skip-term X loads of each half-chunk to the top of the half (one wait instead of 8 load+vmcnt(0) round trips)
# speedup vs baseline: 1.0009x; 1.0009x over previous
; __device__ __forceinline__ unsigned pk2(float lo, float hi) { const f32x2 v = {lo, hi}; const bf16x2_t b = __builtin_convertvector(v, bf16x2_t); return __builtin_bit_cast(unsigned, b); }
; template <int PASS> __device__ __forceinline__ void ssm_phase(int j, LAS unsigned char* lds, int lane, int wave) { KARGS;
;     ...
;                     if (fq < 2) { const int l = 32 * half + 16 * lt + fr; const float rs = rsL[l]; const float* xp = X + (size_t)(64 * c + l) * D + 16 * g + 8 * fq;
;                         const f32x4 x0 = *(const f32x4*)xp * rs, x1 = *(const f32x4*)(xp + 4) * rs;
;                         u32x4 w; w.x = pk2(x0[0], x0[1]); w.y = pk2(x0[2], x0[3]); w.z = pk2(x1[0], x1[1]); w.w = pk2(x1[2], x1[3]); uf = __builtin_bit_cast(bf16x8, w); }
;     ...
;                         for (int r = 0; r < 4; ++r) { const int l = 32 * half + 16 * lt + 4 * fq + r; const size_t t = (size_t)(64 * c + l);
;                             const float v = y[r] + dd * X[t * D + ch] * rsL[l];
.LBB0_343:
	v_or_b32_e32 v134, s70, v72
	v_or_b32_e32 v136, s12, v134
	v_ashrrev_i32_e32 v137, 31, v136
	v_lshlrev_b64 v[136:137], 11, v[136:137]
	v_or_b32_e32 v136, v136, v86
	v_lshl_add_u64 v[136:137], v[136:137], 2, s[60:61]
	global_load_dword v126, v[136:137], off
	v_or_b32_e32 v138, s54, v134
	v_ashrrev_i32_e32 v139, 31, v138
	v_lshlrev_b64 v[138:139], 11, v[138:139]
	v_or_b32_e32 v138, v138, v86
	v_lshl_add_u64 v[138:139], v[138:139], 2, s[60:61]
	global_load_dword v127, v[138:139], off
	v_or_b32_e32 v136, s55, v134
	v_ashrrev_i32_e32 v137, 31, v136
	v_lshlrev_b64 v[136:137], 11, v[136:137]
	v_or_b32_e32 v136, v136, v86
	v_lshl_add_u64 v[136:137], v[136:137], 2, s[60:61]
	global_load_dword v128, v[136:137], off
	v_or_b32_e32 v138, s68, v134
	v_ashrrev_i32_e32 v139, 31, v138
	v_lshlrev_b64 v[138:139], 11, v[138:139]
	v_or_b32_e32 v138, v138, v86
	v_lshl_add_u64 v[138:139], v[138:139], 2, s[60:61]
	global_load_dword v129, v[138:139], off
	v_or_b32_e32 v136, s13, v134
	v_ashrrev_i32_e32 v137, 31, v136
	v_lshlrev_b64 v[136:137], 11, v[136:137]
	v_or_b32_e32 v136, v136, v86
	v_lshl_add_u64 v[136:137], v[136:137], 2, s[60:61]
	global_load_dword v130, v[136:137], off
	v_or_b32_e32 v138, s77, v134
	v_ashrrev_i32_e32 v139, 31, v138
	v_lshlrev_b64 v[138:139], 11, v[138:139]
	v_or_b32_e32 v138, v138, v86
	v_lshl_add_u64 v[138:139], v[138:139], 2, s[60:61]
	global_load_dword v131, v[138:139], off
	v_or_b32_e32 v136, s80, v134
	v_ashrrev_i32_e32 v137, 31, v136
	v_lshlrev_b64 v[136:137], 11, v[136:137]
	v_or_b32_e32 v136, v136, v86
	v_lshl_add_u64 v[136:137], v[136:137], 2, s[60:61]
	global_load_dword v132, v[136:137], off
	v_or_b32_e32 v138, s81, v134
	v_ashrrev_i32_e32 v139, 31, v138
	v_lshlrev_b64 v[138:139], 11, v[138:139]
	v_or_b32_e32 v138, v138, v86
	v_lshl_add_u64 v[138:139], v[138:139], 2, s[60:61]
	global_load_dword v133, v[138:139], off
	v_or_b32_e32 v59, s70, v62
	v_mov_b32_e32 v52, 0
	v_lshl_add_u32 v58, v59, 2, s18
	v_mov_b32_e32 v54, 0
	v_mov_b32_e32 v55, 0
	v_mov_b32_e32 v56, 0
	v_mov_b32_e32 v57, 0
	s_and_saveexec_b64 s[10:11], s[8:9]
	s_cbranch_execz .LBB0_345
	v_or_b32_e32 v54, s12, v59
	v_ashrrev_i32_e32 v55, 31, v54
	v_lshlrev_b64 v[54:55], 13, v[54:55]
	v_lshl_add_u64 v[98:99], v[88:89], 0, v[54:55]
	global_load_dwordx4 v[54:57], v[98:99], off
	s_nop 0
	global_load_dwordx4 v[98:101], v[98:99], off offset:16
	ds_read_b32 v102, v58 offset:16384
	s_waitcnt vmcnt(1) lgkmcnt(0)
	v_pk_mul_f32 v[56:57], v[56:57], v[102:103] op_sel_hi:[1,0]
	v_pk_mul_f32 v[54:55], v[54:55], v[102:103] op_sel_hi:[1,0]
	s_waitcnt vmcnt(0)
	v_pk_mul_f32 v[100:101], v[100:101], v[102:103] op_sel_hi:[1,0]
	v_pk_mul_f32 v[98:99], v[98:99], v[102:103] op_sel_hi:[1,0]
	v_cvt_pk_bf16_f32 v54, v54, v55
	v_cvt_pk_bf16_f32 v55, v56, v57
	v_cvt_pk_bf16_f32 v56, v98, v99
	v_cvt_pk_bf16_f32 v57, v100, v101

; #define LAS __attribute__((address_space(3)))
; __device__ __forceinline__ unsigned pk2(float lo, float hi) { const f32x2 v = {lo, hi}; const bf16x2_t b = __builtin_convertvector(v, bf16x2_t); return __builtin_bit_cast(unsigned, b); }
; template <int PASS> __device__ __forceinline__ void ssm_phase(int j, LAS unsigned char* lds, int lane, int wave) { KARGS;
;     ...
;                 for (int l8 = 0; l8 < 32; l8 += 8) {
;                     unsigned w[8];
; #pragma unroll
;                     for (int q = 0; q < 8; ++q) w[q] = *(const LAS unsigned*)(buL + (l8 + q) * 256 + 4 * p);
; #pragma unroll
;                     for (int q = 0; q < 8; ++q) {
;                         const float nr = abr * hr - abi * hi + bflo(w[q]), ni = abr * hi + abi * hr + bfhi(w[q]); hr = nr; hi = ni;
;                         if (PASS == 3) *(LAS unsigned*)(hL + (l8 + q) * 256 + ((((p >> 2) ^ ((l8 + q) & 15))) << 4) + (p & 3) * 4) = pk2(hr, hi);
;                     }
;                 }
.LBB0_348:
	v_add_u32_e32 v52, s15, v56
	ds_read2st64_b32 v[58:59], v52 offset1:1
	ds_read2st64_b32 v[98:99], v52 offset0:2 offset1:3
	ds_read2st64_b32 v[54:55], v52 offset0:4 offset1:5
	ds_read2st64_b32 v[52:53], v52 offset0:6 offset1:7
	v_pk_mul_f32 v[102:103], v[84:85], v[0:1]
	s_add_i32 s5, s4, 8
	v_pk_fma_f32 v[104:105], v[2:3], v[0:1], v[102:103] op_sel:[0,0,1] op_sel_hi:[1,1,0] neg_lo:[0,0,1] neg_hi:[0,0,1]
	v_pk_fma_f32 v[0:1], v[2:3], v[0:1], v[102:103] op_sel:[0,0,1] op_sel_hi:[1,1,0]
	s_waitcnt lgkmcnt(3)
	v_lshlrev_b32_e32 v100, 16, v58
	v_and_b32_e32 v101, 0xffff0000, v58
	v_mov_b32_e32 v105, v1
	v_pk_add_f32 v[0:1], v[104:105], v[100:101]
	v_bitop3_b32 v97, s5, v63, 8 bitop3:0x6c
	v_lshlrev_b32_e32 v97, 4, v97
	v_pk_mul_f32 v[100:101], v[84:85], v[0:1]
	v_cvt_pk_bf16_f32 v58, v0, v1
	v_add3_u32 v97, s15, v97, v57
	v_pk_fma_f32 v[102:103], v[2:3], v[0:1], v[100:101] op_sel:[0,0,1] op_sel_hi:[1,1,0] neg_lo:[0,0,1] neg_hi:[0,0,1]
	v_pk_fma_f32 v[0:1], v[2:3], v[0:1], v[100:101] op_sel:[0,0,1] op_sel_hi:[1,1,0]
	ds_write_b32 v97, v58
	v_lshlrev_b32_e32 v58, 16, v59
	v_and_b32_e32 v59, 0xffff0000, v59
	v_mov_b32_e32 v103, v1
	s_add_i32 s38, s4, 9
	v_pk_add_f32 v[0:1], v[102:103], v[58:59]
	v_bitop3_b32 v59, s38, v63, 9 bitop3:0x6c
	v_lshlrev_b32_e32 v59, 4, v59
	v_pk_mul_f32 v[100:101], v[84:85], v[0:1]
	v_cvt_pk_bf16_f32 v58, v0, v1
	v_add3_u32 v59, s15, v59, v57
	v_pk_fma_f32 v[102:103], v[2:3], v[0:1], v[100:101] op_sel:[0,0,1] op_sel_hi:[1,1,0] neg_lo:[0,0,1] neg_hi:[0,0,1]
	v_pk_fma_f32 v[0:1], v[2:3], v[0:1], v[100:101] op_sel:[0,0,1] op_sel_hi:[1,1,0]
	ds_write_b32 v59, v58 offset:256
	s_waitcnt lgkmcnt(4)
	v_lshlrev_b32_e32 v58, 16, v98
	v_and_b32_e32 v59, 0xffff0000, v98
	v_mov_b32_e32 v103, v1
	s_add_i32 s38, s4, 10
	v_pk_add_f32 v[0:1], v[102:103], v[58:59]
	v_bitop3_b32 v59, s38, v63, 10 bitop3:0x6c
	v_lshlrev_b32_e32 v59, 4, v59
	v_cvt_pk_bf16_f32 v58, v0, v1
	v_add3_u32 v59, s15, v59, v57
	ds_write_b32 v59, v58 offset:512
	v_lshlrev_b32_e32 v58, 16, v99
	v_and_b32_e32 v59, 0xffff0000, v99
	v_pk_mul_f32 v[98:99], v[84:85], v[0:1]
	s_add_i32 s38, s4, 11
	v_pk_fma_f32 v[100:101], v[2:3], v[0:1], v[98:99] op_sel:[0,0,1] op_sel_hi:[1,1,0] neg_lo:[0,0,1] neg_hi:[0,0,1]
	v_pk_fma_f32 v[0:1], v[2:3], v[0:1], v[98:99] op_sel:[0,0,1] op_sel_hi:[1,1,0]
	v_add_u32_e32 v56, 0x800, v56
	v_mov_b32_e32 v101, v1
	v_pk_add_f32 v[0:1], v[100:101], v[58:59]
	v_bitop3_b32 v59, s38, v63, 11 bitop3:0x6c
	v_lshlrev_b32_e32 v59, 4, v59
	v_pk_mul_f32 v[98:99], v[84:85], v[0:1]
	v_cvt_pk_bf16_f32 v58, v0, v1
	v_add3_u32 v59, s15, v59, v57
	v_pk_fma_f32 v[100:101], v[2:3], v[0:1], v[98:99] op_sel:[0,0,1] op_sel_hi:[1,1,0] neg_lo:[0,0,1] neg_hi:[0,0,1]
	v_pk_fma_f32 v[0:1], v[2:3], v[0:1], v[98:99] op_sel:[0,0,1] op_sel_hi:[1,1,0]
	s_add_i32 s38, s4, 12
	ds_write_b32 v59, v58 offset:768
	s_waitcnt lgkmcnt(5)
	v_lshlrev_b32_e32 v58, 16, v54
	v_mov_b32_e32 v101, v1
	v_and_b32_e32 v59, 0xffff0000, v54
	v_bitop3_b32 v0, s38, v63, 12 bitop3:0x6c
	v_lshlrev_b32_e32 v0, 4, v0
	v_pk_add_f32 v[58:59], v[100:101], v[58:59]
	v_add3_u32 v97, s15, v0, v57
	v_cvt_pk_bf16_f32 v98, v58, v59
	ds_write_b32 v97, v98 offset:1024
	v_pk_mul_f32 v[98:99], v[84:85], v[58:59]
	s_add_i32 s38, s4, 13
	v_pk_fma_f32 v[100:101], v[2:3], v[58:59], v[98:99] op_sel:[0,0,1] op_sel_hi:[1,1,0] neg_lo:[0,0,1] neg_hi:[0,0,1]
	v_pk_fma_f32 v[58:59], v[2:3], v[58:59], v[98:99] op_sel:[0,0,1] op_sel_hi:[1,1,0]
	v_lshlrev_b32_e32 v0, 16, v55
	v_and_b32_e32 v1, 0xffff0000, v55
	v_bitop3_b32 v54, s38, v63, 13 bitop3:0x6c
	v_mov_b32_e32 v101, v59
	v_lshlrev_b32_e32 v54, 4, v54
	v_pk_add_f32 v[0:1], v[100:101], v[0:1]
	v_add3_u32 v102, s15, v54, v57
	v_cvt_pk_bf16_f32 v58, v0, v1
	ds_write_b32 v102, v58 offset:1280
	v_pk_mul_f32 v[58:59], v[84:85], v[0:1]
	s_add_i32 s38, s4, 14
	v_pk_fma_f32 v[98:99], v[2:3], v[0:1], v[58:59] op_sel:[0,0,1] op_sel_hi:[1,1,0] neg_lo:[0,0,1] neg_hi:[0,0,1]
	v_pk_fma_f32 v[0:1], v[2:3], v[0:1], v[58:59] op_sel:[0,0,1] op_sel_hi:[1,1,0]
	s_waitcnt lgkmcnt(6)
	v_lshlrev_b32_e32 v54, 16, v52
	v_and_b32_e32 v55, 0xffff0000, v52
	v_bitop3_b32 v52, s38, v63, 14 bitop3:0x6c
	v_mov_b32_e32 v99, v1
	v_lshlrev_b32_e32 v52, 4, v52
	v_pk_add_f32 v[0:1], v[98:99], v[54:55]
	v_add3_u32 v103, s15, v52, v57
	v_cvt_pk_bf16_f32 v54, v0, v1
	ds_write_b32 v103, v54 offset:1536
	v_pk_mul_f32 v[54:55], v[84:85], v[0:1]
	v_lshlrev_b32_e32 v52, 16, v53
	v_pk_fma_f32 v[58:59], v[2:3], v[0:1], v[54:55] op_sel:[0,0,1] op_sel_hi:[1,1,0] neg_lo:[0,0,1] neg_hi:[0,0,1]
	v_pk_fma_f32 v[0:1], v[2:3], v[0:1], v[54:55] op_sel:[0,0,1] op_sel_hi:[1,1,0]
	v_and_b32_e32 v53, 0xffff0000, v53
	v_mov_b32_e32 v59, v1
	s_add_i32 s4, s4, -1
	v_pk_add_f32 v[0:1], v[58:59], v[52:53]
	v_bitop3_b32 v53, s4, v63, 15 bitop3:0x6c
	v_lshlrev_b32_e32 v53, 4, v53
	v_cvt_pk_bf16_f32 v52, v0, v1
	v_add3_u32 v53, s15, v53, v57
	v_add_u32_e32 v57, 0x800, v57
	s_cmp_gt_u32 s5, 23
	s_mov_b32 s4, s5
	ds_write_b32 v53, v52 offset:1792
	s_cbranch_scc0 .LBB0_348
; #define LAS __attribute__((address_space(3)))
; __device__ __forceinline__ unsigned f2bf(float f) { unsigned u = __builtin_bit_cast(unsigned, f); return (u + 0x7fffu + ((u >> 16) & 1u)) >> 16; }
; __device__ __forceinline__ float gelu_tanh(float v) { const float z = 0.7978845608028654f * (v + 0.044715f * v * v * v); return v * (1.0f - 1.0f / (1.0f + __expf(2.0f * z))); }
; template <int PASS> __device__ __forceinline__ void ssm_phase(int j, LAS unsigned char* lds, int lane, int wave) { KARGS;
;     ...
;                 if (PASS == 3) {
; #pragma unroll
;                     for (int lt = 0; lt < 2; ++lt) {
;                         f32x4 y = {0.f, 0.f, 0.f, 0.f};
; #pragma unroll
;                         for (int ks = 0; ks < 4; ++ks) { const bf16x8 hf = *(const LAS bf16x8*)(hL + (16 * lt + fr) * 256 + (((4 * ks + fq) ^ fr) << 4)); y = __builtin_amdgcn_mfma_f32_16x16x32_bf16(hf, cf[ks], y, 0, 0, 0); }
;                         asm volatile("s_nop 15\n\ts_nop 15" : "+v"(y));
;                         const int ch = 16 * g + fr;
; #pragma unroll
;                         for (int r = 0; r < 4; ++r) { const int l = 32 * half + 16 * lt + 4 * fq + r; const size_t t = (size_t)(64 * c + l);
;                             const float v = y[r] + dd * X[t * D + ch] * rsL[l];
;                             GL[t * D + ch] = (bf16_t)f2bf(gelu_tanh(v)); }
;                     }
	s_waitcnt lgkmcnt(0)
	ds_read_b128 v[52:55], v87
	ds_read_b128 v[56:59], v92
	v_or_b32_e32 v97, s70, v72
	v_lshl_add_u32 v98, v97, 2, s18
	s_mov_b32 s70, 32
	s_waitcnt lgkmcnt(1)
	v_mfma_f32_16x16x32_bf16 v[52:55], v[52:55], v[36:39], 0
	s_waitcnt lgkmcnt(0)
	v_mfma_f32_16x16x32_bf16 v[52:55], v[56:59], v[40:43], v[52:55]
	ds_read_b128 v[56:59], v93
	s_waitcnt lgkmcnt(0)
	v_mfma_f32_16x16x32_bf16 v[52:55], v[56:59], v[44:47], v[52:55]
	ds_read_b128 v[56:59], v94
	s_waitcnt lgkmcnt(0)
	v_mfma_f32_16x16x32_bf16 v[52:55], v[56:59], v[48:51], v[52:55]
	v_or_b32_e32 v56, s12, v97
	v_ashrrev_i32_e32 v57, 31, v56
	v_lshlrev_b64 v[100:101], 11, v[56:57]
	v_or_b32_e32 v100, v100, v86
	v_lshl_add_u64 v[56:57], v[100:101], 2, s[60:61]
	s_nop 15
	s_nop 15
	v_lshl_add_u64 v[100:101], v[100:101], 1, s[64:65]
	s_waitcnt vmcnt(0)
	v_mul_f32_e32 v99, v83, v126
	ds_read_b128 v[56:59], v98 offset:16384
	s_waitcnt lgkmcnt(0)
	v_fma_f32 v52, v99, v56, v52
	v_mul_f32_e32 v56, 0x3d372713, v52
	v_mul_f32_e32 v56, v52, v56
	v_fma_f32 v56, v52, v56, v52
	v_mul_f32_e32 v56, 0x3f4c422a, v56
	v_add_f32_e32 v56, v56, v56
	v_mul_f32_e32 v56, 0x3fb8aa3b, v56
	v_exp_f32_e32 v56, v56
	s_nop 0
	v_add_f32_e32 v56, 1.0, v56
	v_div_scale_f32 v99, s[4:5], v56, v56, 1.0
	v_rcp_f32_e32 v102, v99
	s_nop 0
	v_fma_f32 v103, -v99, v102, 1.0
	v_fmac_f32_e32 v102, v103, v102
	v_div_scale_f32 v103, vcc, 1.0, v56, 1.0
	v_mul_f32_e32 v104, v103, v102
	v_fma_f32 v105, -v99, v104, v103
	v_fmac_f32_e32 v104, v105, v102
	v_fma_f32 v99, -v99, v104, v103
	v_div_fmas_f32 v99, v99, v102, v104
	v_div_fixup_f32 v56, v99, v56, 1.0
	v_sub_f32_e32 v56, 1.0, v56
	v_mul_f32_e32 v52, v52, v56
	v_bfe_u32 v56, v52, 16, 1
	v_add3_u32 v52, v52, v56, s75
	global_store_short_d16_hi v[100:101], v52, off
	v_or_b32_e32 v100, s54, v97
	v_ashrrev_i32_e32 v101, 31, v100
	v_lshlrev_b64 v[100:101], 11, v[100:101]
	v_or_b32_e32 v100, v100, v86
	v_lshl_add_u64 v[102:103], v[100:101], 2, s[60:61]
	v_mul_f32_e32 v52, v83, v127
	v_fma_f32 v52, v52, v57, v53
	v_mul_f32_e32 v53, 0x3d372713, v52
	v_mul_f32_e32 v53, v52, v53
	v_fma_f32 v53, v52, v53, v52
	v_mul_f32_e32 v53, 0x3f4c422a, v53
	v_add_f32_e32 v53, v53, v53
	v_mul_f32_e32 v53, 0x3fb8aa3b, v53
	v_exp_f32_e32 v53, v53
	s_nop 0
	v_add_f32_e32 v53, 1.0, v53
	v_div_scale_f32 v56, s[4:5], v53, v53, 1.0
	v_rcp_f32_e32 v57, v56
	s_nop 0
	v_fma_f32 v99, -v56, v57, 1.0
	v_fmac_f32_e32 v57, v99, v57
	v_div_scale_f32 v99, vcc, 1.0, v53, 1.0
	v_mul_f32_e32 v102, v99, v57
	v_fma_f32 v103, -v56, v102, v99
	v_fmac_f32_e32 v102, v103, v57
	v_fma_f32 v56, -v56, v102, v99
	v_div_fmas_f32 v56, v56, v57, v102
	v_div_fixup_f32 v53, v56, v53, 1.0
	v_sub_f32_e32 v53, 1.0, v53
	v_mul_f32_e32 v52, v52, v53
	v_bfe_u32 v53, v52, 16, 1
	v_add3_u32 v56, v52, v53, s75
	v_lshl_add_u64 v[52:53], v[100:101], 1, s[64:65]
	global_store_short_d16_hi v[52:53], v56, off
	v_or_b32_e32 v52, s55, v97
	v_ashrrev_i32_e32 v53, 31, v52
	v_lshlrev_b64 v[52:53], 11, v[52:53]
	v_or_b32_e32 v52, v52, v86
	v_lshl_add_u64 v[56:57], v[52:53], 2, s[60:61]
	v_lshl_add_u64 v[52:53], v[52:53], 1, s[64:65]
	v_mul_f32_e32 v56, v83, v128
	v_fma_f32 v54, v56, v58, v54
	v_mul_f32_e32 v56, 0x3d372713, v54
	v_mul_f32_e32 v56, v54, v56
	v_fma_f32 v56, v54, v56, v54
	v_mul_f32_e32 v56, 0x3f4c422a, v56
	v_add_f32_e32 v56, v56, v56
	v_mul_f32_e32 v56, 0x3fb8aa3b, v56
	v_exp_f32_e32 v56, v56
	s_nop 0
	v_add_f32_e32 v56, 1.0, v56
	v_div_scale_f32 v57, s[4:5], v56, v56, 1.0
	v_rcp_f32_e32 v58, v57
	s_nop 0
	v_fma_f32 v99, -v57, v58, 1.0
	v_fmac_f32_e32 v58, v99, v58
	v_div_scale_f32 v99, vcc, 1.0, v56, 1.0
	v_mul_f32_e32 v100, v99, v58
	v_fma_f32 v101, -v57, v100, v99
	v_fmac_f32_e32 v100, v101, v58
	v_fma_f32 v57, -v57, v100, v99
	v_div_fmas_f32 v57, v57, v58, v100
	v_div_fixup_f32 v56, v57, v56, 1.0
	v_sub_f32_e32 v56, 1.0, v56
	v_mul_f32_e32 v54, v54, v56
	v_bfe_u32 v56, v54, 16, 1
	v_add3_u32 v54, v54, v56, s75
	global_store_short_d16_hi v[52:53], v54, off
	v_or_b32_e32 v52, s68, v97
	v_ashrrev_i32_e32 v53, 31, v52
	v_lshlrev_b64 v[52:53], 11, v[52:53]
	v_or_b32_e32 v52, v52, v86
	v_lshl_add_u64 v[56:57], v[52:53], 2, s[60:61]
	v_lshl_add_u64 v[52:53], v[52:53], 1, s[64:65]
	v_mul_f32_e32 v54, v83, v129
	v_fmac_f32_e32 v55, v54, v59
	v_mul_f32_e32 v54, 0x3d372713, v55
	v_mul_f32_e32 v54, v55, v54
	v_fma_f32 v54, v55, v54, v55
	v_mul_f32_e32 v54, 0x3f4c422a, v54
	v_add_f32_e32 v54, v54, v54
	v_mul_f32_e32 v54, 0x3fb8aa3b, v54
	v_exp_f32_e32 v54, v54
	s_nop 0
	v_add_f32_e32 v54, 1.0, v54
	v_div_scale_f32 v56, s[4:5], v54, v54, 1.0
	v_rcp_f32_e32 v57, v56
	s_nop 0
	v_fma_f32 v58, -v56, v57, 1.0
	v_fmac_f32_e32 v57, v58, v57
	v_div_scale_f32 v58, vcc, 1.0, v54, 1.0
	v_mul_f32_e32 v59, v58, v57
	v_fma_f32 v99, -v56, v59, v58
	v_fmac_f32_e32 v59, v99, v57
	v_fma_f32 v56, -v56, v59, v58
	v_div_fmas_f32 v56, v56, v57, v59
	v_div_fixup_f32 v54, v56, v54, 1.0
	v_sub_f32_e32 v54, 1.0, v54
	v_mul_f32_e32 v54, v55, v54
	v_bfe_u32 v55, v54, 16, 1
	v_add3_u32 v54, v54, v55, s75
	global_store_short_d16_hi v[52:53], v54, off
	ds_read_b128 v[52:55], v87 offset:4096
	ds_read_b128 v[56:59], v92 offset:4096
	s_waitcnt lgkmcnt(1)
; #define LAS __attribute__((address_space(3)))
; __device__ __forceinline__ unsigned f2bf(float f) { unsigned u = __builtin_bit_cast(unsigned, f); return (u + 0x7fffu + ((u >> 16) & 1u)) >> 16; }
; __device__ __forceinline__ float gelu_tanh(float v) { const float z = 0.7978845608028654f * (v + 0.044715f * v * v * v); return v * (1.0f - 1.0f / (1.0f + __expf(2.0f * z))); }
; template <int PASS> __device__ __forceinline__ void ssm_phase(int j, LAS unsigned char* lds, int lane, int wave) { KARGS;
;     ...
;                 if (PASS == 3) {
; #pragma unroll
;                     for (int lt = 0; lt < 2; ++lt) {
;                         f32x4 y = {0.f, 0.f, 0.f, 0.f};
; #pragma unroll
;                         for (int ks = 0; ks < 4; ++ks) { const bf16x8 hf = *(const LAS bf16x8*)(hL + (16 * lt + fr) * 256 + (((4 * ks + fq) ^ fr) << 4)); y = __builtin_amdgcn_mfma_f32_16x16x32_bf16(hf, cf[ks], y, 0, 0, 0); }
;                         asm volatile("s_nop 15\n\ts_nop 15" : "+v"(y));
;                         const int ch = 16 * g + fr;
; #pragma unroll
;                         for (int r = 0; r < 4; ++r) { const int l = 32 * half + 16 * lt + 4 * fq + r; const size_t t = (size_t)(64 * c + l);
;                             const float v = y[r] + dd * X[t * D + ch] * rsL[l];
;                             GL[t * D + ch] = (bf16_t)f2bf(gelu_tanh(v)); }
;                     }
	v_mfma_f32_16x16x32_bf16 v[52:55], v[52:55], v[36:39], 0
	s_waitcnt lgkmcnt(0)
	v_mfma_f32_16x16x32_bf16 v[52:55], v[56:59], v[40:43], v[52:55]
	ds_read_b128 v[56:59], v93 offset:4096
	s_waitcnt lgkmcnt(0)
	v_mfma_f32_16x16x32_bf16 v[52:55], v[56:59], v[44:47], v[52:55]
	ds_read_b128 v[56:59], v94 offset:4096
	s_waitcnt lgkmcnt(0)
	v_mfma_f32_16x16x32_bf16 v[52:55], v[56:59], v[48:51], v[52:55]
	v_or_b32_e32 v56, s13, v97
	v_ashrrev_i32_e32 v57, 31, v56
	v_lshlrev_b64 v[100:101], 11, v[56:57]
	v_or_b32_e32 v100, v100, v86
	v_lshl_add_u64 v[56:57], v[100:101], 2, s[60:61]
	s_nop 15
	s_nop 15
	v_mul_f32_e32 v99, v83, v130
	ds_read_b128 v[56:59], v98 offset:16448
	s_waitcnt lgkmcnt(0)
	v_fma_f32 v52, v99, v56, v52
	v_mul_f32_e32 v56, 0x3d372713, v52
	v_mul_f32_e32 v56, v52, v56
	v_fma_f32 v56, v52, v56, v52
	v_mul_f32_e32 v56, 0x3f4c422a, v56
	v_add_f32_e32 v56, v56, v56
	v_mul_f32_e32 v56, 0x3fb8aa3b, v56
	v_exp_f32_e32 v56, v56
	s_nop 0
	v_add_f32_e32 v56, 1.0, v56
	v_div_scale_f32 v98, s[4:5], v56, v56, 1.0
	v_rcp_f32_e32 v99, v98
	s_nop 0
	v_fma_f32 v102, -v98, v99, 1.0
	v_fmac_f32_e32 v99, v102, v99
	v_div_scale_f32 v102, vcc, 1.0, v56, 1.0
	v_mul_f32_e32 v103, v102, v99
	v_fma_f32 v104, -v98, v103, v102
	v_fmac_f32_e32 v103, v104, v99
	v_fma_f32 v98, -v98, v103, v102
	v_div_fmas_f32 v98, v98, v99, v103
	v_div_fixup_f32 v56, v98, v56, 1.0
	v_sub_f32_e32 v56, 1.0, v56
	v_mul_f32_e32 v52, v52, v56
	v_bfe_u32 v56, v52, 16, 1
	v_add3_u32 v52, v52, v56, s75
	v_lshl_add_u64 v[98:99], v[100:101], 1, s[64:65]
	global_store_short_d16_hi v[98:99], v52, off
	v_or_b32_e32 v98, s77, v97
	v_ashrrev_i32_e32 v99, 31, v98
	v_lshlrev_b64 v[98:99], 11, v[98:99]
	v_or_b32_e32 v98, v98, v86
	v_lshl_add_u64 v[100:101], v[98:99], 2, s[60:61]
	v_mul_f32_e32 v52, v83, v131
	v_fma_f32 v52, v52, v57, v53
	v_mul_f32_e32 v53, 0x3d372713, v52
	v_mul_f32_e32 v53, v52, v53
	v_fma_f32 v53, v52, v53, v52
	v_mul_f32_e32 v53, 0x3f4c422a, v53
	v_add_f32_e32 v53, v53, v53
	v_mul_f32_e32 v53, 0x3fb8aa3b, v53
	v_exp_f32_e32 v53, v53
	s_nop 0
	v_add_f32_e32 v53, 1.0, v53
	v_div_scale_f32 v56, s[4:5], v53, v53, 1.0
	v_rcp_f32_e32 v57, v56
	s_nop 0
	v_fma_f32 v100, -v56, v57, 1.0
	v_fmac_f32_e32 v57, v100, v57
	v_div_scale_f32 v100, vcc, 1.0, v53, 1.0
	v_mul_f32_e32 v101, v100, v57
	v_fma_f32 v102, -v56, v101, v100
	v_fmac_f32_e32 v101, v102, v57
	v_fma_f32 v56, -v56, v101, v100
	v_div_fmas_f32 v56, v56, v57, v101
	v_div_fixup_f32 v53, v56, v53, 1.0
	v_sub_f32_e32 v53, 1.0, v53
	v_mul_f32_e32 v52, v52, v53
	v_bfe_u32 v53, v52, 16, 1
	v_add3_u32 v56, v52, v53, s75
	v_lshl_add_u64 v[52:53], v[98:99], 1, s[64:65]
	global_store_short_d16_hi v[52:53], v56, off
	v_or_b32_e32 v52, s80, v97
	v_ashrrev_i32_e32 v53, 31, v52
	v_lshlrev_b64 v[52:53], 11, v[52:53]
	v_or_b32_e32 v52, v52, v86
	v_lshl_add_u64 v[56:57], v[52:53], 2, s[60:61]
	v_lshl_add_u64 v[52:53], v[52:53], 1, s[64:65]
	v_mul_f32_e32 v56, v83, v132
	v_fma_f32 v54, v56, v58, v54
	v_mul_f32_e32 v56, 0x3d372713, v54
	v_mul_f32_e32 v56, v54, v56
	v_fma_f32 v56, v54, v56, v54
	v_mul_f32_e32 v56, 0x3f4c422a, v56
	v_add_f32_e32 v56, v56, v56
	v_mul_f32_e32 v56, 0x3fb8aa3b, v56
	v_exp_f32_e32 v56, v56
	s_nop 0
	v_add_f32_e32 v56, 1.0, v56
	v_div_scale_f32 v57, s[4:5], v56, v56, 1.0
	v_rcp_f32_e32 v58, v57
	s_nop 0
	v_fma_f32 v98, -v57, v58, 1.0
	v_fmac_f32_e32 v58, v98, v58
	v_div_scale_f32 v98, vcc, 1.0, v56, 1.0
	v_mul_f32_e32 v99, v98, v58
	v_fma_f32 v100, -v57, v99, v98
	v_fmac_f32_e32 v99, v100, v58
	v_fma_f32 v57, -v57, v99, v98
	v_div_fmas_f32 v57, v57, v58, v99
	v_div_fixup_f32 v56, v57, v56, 1.0
	v_sub_f32_e32 v56, 1.0, v56
	v_mul_f32_e32 v54, v54, v56
	v_bfe_u32 v56, v54, 16, 1
	v_add3_u32 v54, v54, v56, s75
	global_store_short_d16_hi v[52:53], v54, off
	v_or_b32_e32 v52, s81, v97
	v_ashrrev_i32_e32 v53, 31, v52
	v_lshlrev_b64 v[52:53], 11, v[52:53]
	v_or_b32_e32 v52, v52, v86
	v_lshl_add_u64 v[56:57], v[52:53], 2, s[60:61]
	v_lshl_add_u64 v[52:53], v[52:53], 1, s[64:65]
	v_mul_f32_e32 v54, v83, v133
	v_fmac_f32_e32 v55, v54, v59
	v_mul_f32_e32 v54, 0x3d372713, v55
	v_mul_f32_e32 v54, v55, v54
	v_fma_f32 v54, v55, v54, v55
	v_mul_f32_e32 v54, 0x3f4c422a, v54
	v_add_f32_e32 v54, v54, v54
	v_mul_f32_e32 v54, 0x3fb8aa3b, v54
	v_exp_f32_e32 v54, v54
	s_nop 0
	v_add_f32_e32 v54, 1.0, v54
	v_div_scale_f32 v56, s[4:5], v54, v54, 1.0
	v_rcp_f32_e32 v57, v56
	s_mov_b64 s[4:5], 0
	v_fma_f32 v58, -v56, v57, 1.0
	v_fmac_f32_e32 v57, v58, v57
	v_div_scale_f32 v58, vcc, 1.0, v54, 1.0
	v_mul_f32_e32 v59, v58, v57
	v_fma_f32 v97, -v56, v59, v58
	v_fmac_f32_e32 v59, v97, v57
	v_fma_f32 v56, -v56, v59, v58
	v_div_fmas_f32 v56, v56, v57, v59
	v_div_fixup_f32 v54, v56, v54, 1.0
	v_sub_f32_e32 v54, 1.0, v54
	v_mul_f32_e32 v54, v55, v54
	v_bfe_u32 v55, v54, 16, 1
	v_add3_u32 v54, v54, v55, s75
	global_store_short_d16_hi v[52:53], v54, off
	s_waitcnt lgkmcnt(0)
	s_and_b64 vcc, exec, s[10:11]
	s_cbranch_vccz .LBB0_343
	s_cmpk_lg_i32 s53, 0x7f
	s_cbranch_scc0 .LBB0_354
	s_cmpk_gt_i32 s53, 0x7f
	s_mov_b64 s[12:13], 0
	s_cbranch_scc1 .LBB0_355
	s_and_b64 vcc, exec, s[4:5]
	v_lshlrev_b32_e32 v192, 2, v60
	s_cbranch_vccnz .LBB0_356
